# grid-barrier polling: s_sleep 24 -> s_sleep 8 at the 12 poll sites
# speedup vs baseline: 1.0012x; 1.0012x over previous
; DI void grid_barrier(unsigned* cnt, unsigned target) {
;   asm volatile("s_waitcnt vmcnt(0) lgkmcnt(0)" ::: "memory");
;   __syncthreads();
;   if (threadIdx.x == 0) {
;     __threadfence();
;     __hip_atomic_fetch_add(cnt, 1u, __ATOMIC_RELAXED, __HIP_MEMORY_SCOPE_AGENT);
;     while (__hip_atomic_load(cnt, __ATOMIC_RELAXED, __HIP_MEMORY_SCOPE_AGENT) < target) __builtin_amdgcn_s_sleep(24);
;     __threadfence();
;   }
;   __syncthreads();
; }
.LBB0_8:
	s_sleep 8
	global_load_dword v2, v1, s[96:97] sc1
	s_waitcnt vmcnt(0)
	v_cmp_gt_u32_e32 vcc, s3, v2
	s_cbranch_vccnz .LBB0_8

; DI void grid_barrier(unsigned* cnt, unsigned target) {
;   asm volatile("s_waitcnt vmcnt(0) lgkmcnt(0)" ::: "memory");
;   __syncthreads();
;   if (threadIdx.x == 0) {
;     __threadfence();
;     __hip_atomic_fetch_add(cnt, 1u, __ATOMIC_RELAXED, __HIP_MEMORY_SCOPE_AGENT);
;     while (__hip_atomic_load(cnt, __ATOMIC_RELAXED, __HIP_MEMORY_SCOPE_AGENT) < target) __builtin_amdgcn_s_sleep(24);
;     __threadfence();
;   }
;   __syncthreads();
; }
.LBB0_127:
	s_sleep 8
	global_load_dword v2, v1, s[96:97] sc1
	s_waitcnt vmcnt(0)
	v_cmp_gt_u32_e32 vcc, s88, v2
	s_cbranch_vccnz .LBB0_127

; DI void grid_barrier(unsigned* cnt, unsigned target) {
;   asm volatile("s_waitcnt vmcnt(0) lgkmcnt(0)" ::: "memory");
;   __syncthreads();
;   if (threadIdx.x == 0) {
;     __threadfence();
;     __hip_atomic_fetch_add(cnt, 1u, __ATOMIC_RELAXED, __HIP_MEMORY_SCOPE_AGENT);
;     while (__hip_atomic_load(cnt, __ATOMIC_RELAXED, __HIP_MEMORY_SCOPE_AGENT) < target) __builtin_amdgcn_s_sleep(24);
;     __threadfence();
;   }
;   __syncthreads();
; }
.LBB0_186:
	s_sleep 8
	global_load_dword v3, v2, s[96:97] sc1
	s_waitcnt vmcnt(0)
	v_cmp_gt_u32_e32 vcc, s3, v3
	s_cbranch_vccnz .LBB0_186

; DI void grid_barrier(unsigned* cnt, unsigned target) {
;   asm volatile("s_waitcnt vmcnt(0) lgkmcnt(0)" ::: "memory");
;   __syncthreads();
;   if (threadIdx.x == 0) {
;     __threadfence();
;     __hip_atomic_fetch_add(cnt, 1u, __ATOMIC_RELAXED, __HIP_MEMORY_SCOPE_AGENT);
;     while (__hip_atomic_load(cnt, __ATOMIC_RELAXED, __HIP_MEMORY_SCOPE_AGENT) < target) __builtin_amdgcn_s_sleep(24);
;     __threadfence();
;   }
;   __syncthreads();
; }
.LBB0_673:
	s_sleep 8
	global_load_dword v1, v0, s[96:97] sc1
	s_waitcnt vmcnt(0)
	v_cmp_gt_u32_e32 vcc, s3, v1
	s_cbranch_vccnz .LBB0_673
